# v1 + mLSTM latency fixes: conv-weight staging loads batched, dn column sums with batched LDS reads, poll sleep 120->8
# speedup vs baseline: 1.0014x; 1.0014x over previous
; __global__ void __launch_bounds__(512, 2) mega_fwd(Args a) {
;     ...
;                     if (isfox && !((okmask >> xcd) & 1u)) { unsigned sp = 0u;
;                         while (__hip_atomic_load(done, __ATOMIC_RELAXED, __HIP_MEMORY_SCOPE_AGENT) < 48u) { __builtin_amdgcn_s_sleep(120); if (++sp > (1u << 17)) break; }
;                         __builtin_amdgcn_fence(__ATOMIC_ACQUIRE, "agent"); okmask |= 1u << xcd; }
.LBB0_716:
	global_load_dword v1, v3, s[46:47] sc1
	s_mov_b64 s[0:1], -1
	s_waitcnt vmcnt(0)
	v_cmp_lt_u32_e32 vcc, 47, v1
	s_cbranch_vccnz .LBB0_715
	s_sleep 8
	global_load_dword v1, v3, s[46:47] sc1
	s_waitcnt vmcnt(0)
	v_cmp_gt_u32_e32 vcc, 48, v1
	s_cbranch_vccz .LBB0_715
	s_sleep 8
	global_load_dword v1, v3, s[46:47] sc1
	s_waitcnt vmcnt(0)
	v_cmp_gt_u32_e32 vcc, 48, v1
	s_cbranch_vccz .LBB0_715
	s_add_i32 s2, s2, -3
	s_cmp_eq_u32 s2, 0
	s_cselect_b64 s[0:1], -1, 0
	s_sleep 8
	s_branch .LBB0_715

; __global__ void __launch_bounds__(512, 2) mega_fwd(Args a) {
;     ...
;                     if (isc && !((okmask >> (8 + xcd)) & 1u)) { unsigned sp = 0u;
;                         while (__hip_atomic_load(done + 8, __ATOMIC_RELAXED, __HIP_MEMORY_SCOPE_AGENT) < 90u) { __builtin_amdgcn_s_sleep(120); if (++sp > (1u << 17)) break; }
;                         __builtin_amdgcn_fence(__ATOMIC_ACQUIRE, "agent"); okmask |= 1u << (8 + xcd); }
.LBB0_726:
	global_load_dword v1, v3, s[46:47] offset:32 sc1
	s_movk_i32 s33, 0x59
	s_mov_b64 s[50:51], -1
	s_waitcnt vmcnt(0)
	v_cmp_lt_u32_e32 vcc, s33, v1
	s_cbranch_vccnz .LBB0_725
	s_sleep 8
	global_load_dword v1, v3, s[46:47] offset:32 sc1
	s_waitcnt vmcnt(0)
	v_cmp_gt_u32_e32 vcc, s73, v1
	s_cbranch_vccz .LBB0_725
	s_sleep 8
	global_load_dword v1, v3, s[46:47] offset:32 sc1
	s_waitcnt vmcnt(0)
	v_cmp_gt_u32_e32 vcc, s73, v1
	s_cbranch_vccz .LBB0_725
	s_add_i32 s3, s3, -3
	s_cmp_eq_u32 s3, 0
	s_cselect_b64 s[50:51], -1, 0
	s_sleep 8
	s_branch .LBB0_725

; #define LAS __attribute__((address_space(3)))
; template <bool OUT>
; __device__ __forceinline__ void mlstm_item(const bf16* u, bf16* y, float* scratch, const float* convw, const float* ib, const float* fbias, const float* normw, LAS unsigned char* wl, int bh, int c, int lane) {
;     const int b = bh / 6, h = bh % 6, r = lane & 31, hi = lane >> 5;
;     const bf16* ub = u + (size_t)b * S * NU;
;     LAS float* cw = (LAS float*)(wl + ML_CW); LAS float* eb = (LAS float*)(wl + ML_EB); LAS float* nl = (LAS float*)(wl + ML_NL); LAS float* nwl = (LAS float*)(wl + ML_NW);
;     for (int i = lane; i < 512; i += 64) { const int tap = i >> 7, ch = i & 127; cw[i] = convw[tap * 768 + (ch < 64 ? (64 * h + ch) : (384 + 64 * h + (ch - 64)))]; }
;     if (OUT) nwl[lane] = normw[h * 64 + lane];
;     const float ibh = ib[h], fbh = fbias[h];
;     f32x16 X[2][2];
; #pragma unroll
;     for (int a = 0; a < 2; ++a)
; #pragma unroll
;         for (int bb = 0; bb < 2; ++bb)
; #pragma unroll
;             for (int i = 0; i < 16; ++i) X[a][bb][i] = 0.f;
.LBB0_781:
	v_add_u32_e32 v8, s52, v202
	v_lshlrev_b32_e32 v8, 2, v8
	v_add_u32_e32 v9, 0x1000, v8
	v_add_u32_e32 v10, 0x2000, v8
	v_add_u32_e32 v11, 0x3000, v8
	global_load_dword v12, v8, s[44:45] offset:2048
	global_load_dword v13, v8, s[44:45] offset:3584
	global_load_dword v14, v9, s[44:45] offset:1024
	global_load_dword v15, v9, s[44:45] offset:2560
	global_load_dword v16, v10, s[44:45]
	global_load_dword v17, v10, s[44:45] offset:1536
	global_load_dword v18, v10, s[44:45] offset:3072
	global_load_dword v19, v11, s[44:45] offset:512
	s_waitcnt vmcnt(7)
	ds_write_b32 v1, v12
	s_waitcnt vmcnt(6)
	ds_write_b32 v1, v13 offset:256
	s_waitcnt vmcnt(5)
	ds_write_b32 v1, v14 offset:512
	s_waitcnt vmcnt(4)
	ds_write_b32 v1, v15 offset:768
	s_waitcnt vmcnt(3)
	ds_write_b32 v1, v16 offset:1024
	s_waitcnt vmcnt(2)
	ds_write_b32 v1, v17 offset:1280
	s_waitcnt vmcnt(1)
	ds_write_b32 v1, v18 offset:1536
	s_waitcnt vmcnt(0)
	ds_write_b32 v1, v19 offset:1792
	s_or_b64 exec, exec, s[0:1]
	v_or_b32_e32 v2, s52, v202
	v_lshl_add_u64 v[4:5], v[2:3], 2, s[44:45]
	s_lshl_b32 s0, s33, 2
	v_mov_b32_e32 v2, s0
	global_load_dword v4, v[4:5], off offset:256
	s_nop 0
	global_load_dword v1, v2, s[44:45] offset:32
	global_load_dword v225, v2, s[44:45] offset:64
	s_and_b32 s0, s3, 15
	s_xor_b32 s51, s0, 15
	s_cmp_lg_u32 s0, 15
	s_movk_i32 s56, 0x3000
	s_waitcnt vmcnt(2)
	ds_write_b32 v149, v4 offset:17152
	s_cbranch_scc0 .LBB0_785
	s_lshl_b32 s0, s3, 3
	s_and_b32 s0, s0, 0xffffff80
	v_readlane_b32 s1, v255, 4
	v_mov_b32_e32 v226, 0
	s_add_i32 s53, s51, 1
	s_or_b32 s3, s1, s0
	v_mov_b32_e32 v2, 1.0
	v_mov_b32_e32 v4, 0
	v_mov_b32_e32 v5, v226
	v_mov_b32_e32 v6, 0
	v_mov_b32_e32 v7, v226
	v_mov_b32_e32 v8, 0
	v_mov_b32_e32 v9, v226
	v_mov_b32_e32 v10, 0
	v_mov_b32_e32 v11, v226
	v_mov_b32_e32 v12, 0
	v_mov_b32_e32 v13, v226
	v_mov_b32_e32 v14, 0
	v_mov_b32_e32 v15, v226
	v_mov_b32_e32 v16, 0
	v_mov_b32_e32 v17, v226
	v_mov_b32_e32 v18, 0
	v_mov_b32_e32 v19, v226
	v_mov_b32_e32 v20, 0
	v_mov_b32_e32 v21, v226
	v_mov_b32_e32 v22, 0
	v_mov_b32_e32 v23, v226
	v_mov_b32_e32 v24, 0
	v_mov_b32_e32 v25, v226
	v_mov_b32_e32 v26, 0
	v_mov_b32_e32 v27, v226
	v_mov_b32_e32 v28, 0
	v_mov_b32_e32 v29, v226
	v_mov_b32_e32 v30, 0
	v_mov_b32_e32 v31, v226
	v_mov_b32_e32 v32, 0
	v_mov_b32_e32 v33, v226
	v_mov_b32_e32 v34, 0
	v_mov_b32_e32 v35, v226
	v_mov_b32_e32 v36, 0
	v_mov_b32_e32 v37, v226
	v_mov_b32_e32 v38, 0
	v_mov_b32_e32 v39, v226
	v_mov_b32_e32 v40, 0
	v_mov_b32_e32 v41, v226
	v_mov_b32_e32 v42, 0
	v_mov_b32_e32 v43, v226
	v_mov_b32_e32 v44, 0
	v_mov_b32_e32 v45, v226
	v_mov_b32_e32 v46, 0
	v_mov_b32_e32 v47, v226
	v_mov_b32_e32 v48, 0
	v_mov_b32_e32 v49, v226
	v_mov_b32_e32 v50, 0
	v_mov_b32_e32 v51, v226
	v_mov_b32_e32 v52, 0
	v_mov_b32_e32 v53, v226
	v_mov_b32_e32 v54, 0
	v_mov_b32_e32 v55, v226
	v_mov_b32_e32 v56, 0
	v_mov_b32_e32 v57, v226
	v_mov_b32_e32 v58, 0
	v_mov_b32_e32 v59, v226
	v_mov_b32_e32 v60, 0
	v_mov_b32_e32 v61, v226
	v_mov_b32_e32 v62, 0
	v_mov_b32_e32 v63, v226
	v_mov_b32_e32 v64, 0
	v_mov_b32_e32 v65, v226
	v_mov_b32_e32 v66, 0
	v_mov_b32_e32 v67, v226

; #define LAS __attribute__((address_space(3)))
; __device__ __forceinline__ float bf2f(unsigned short v) { return __uint_as_float(((unsigned)v) << 16); }
; __device__ __forceinline__ float lo_f(unsigned w) { return __uint_as_float(w << 16); }
; __device__ __forceinline__ float hi_f(unsigned w) { return __uint_as_float(w & 0xffff0000u); }
; __device__ __forceinline__ s16x4 tr_read(LAS const unsigned char* p) { return __builtin_bit_cast(s16x4, __builtin_amdgcn_ds_read_tr16_b64_v4i16((LAS s16x4*)p)); }
; __device__ __forceinline__ s16x8 cat8(s16x4 a, s16x4 b) { return (s16x8){a[0], a[1], a[2], a[3], b[0], b[1], b[2], b[3]}; }
; __device__ __forceinline__ unsigned cvtpk(float lo, float hi) { return pg8::cvt_pk_bf16(lo, hi); }
; #define MFMA32(a, b, c) __builtin_amdgcn_mfma_f32_32x32x16_bf16(a, b, c, 0, 0, 0)
; template <bool OUT>
; __device__ __forceinline__ void mlstm_item(const bf16* u, bf16* y, float* scratch, const float* convw, const float* ib, const float* fbias, const float* normw, LAS unsigned char* wl, int bh, int c, int lane) {
;     ...
;         { const float wsc = __expf(g + es), eg = __expf(g);
; #pragma unroll
;           for (int f = 0; f < 4; ++f) { const v4u kw = __builtin_bit_cast(v4u, Kf[f]);
; #pragma unroll
;               for (int e = 0; e < 2; ++e) { const unsigned k0 = e ? kw.z : kw.x, k1 = e ? kw.w : kw.y; const int ch = 16 * f + 8 * e + 4 * hi;
;                   *(LAS unsigned long long*)(wl + ML_WK + r * 144 + ch * 2) = (unsigned long long)cvtpk(lo_f(k0) * wsc, hi_f(k0) * wsc) | ((unsigned long long)cvtpk(lo_f(k1) * wsc, hi_f(k1) * wsc) << 32); } }
; #pragma unroll
;           for (int kb = 0; kb < 2; ++kb)
; #pragma unroll
;               for (int vb = 0; vb < 2; ++vb) { X[kb][vb] *= eg;
; #pragma unroll
;                   for (int sp = 0; sp < 2; ++sp) { LAS const unsigned char* kp = wl + ML_WK + trN + 16 * sp * 144 + 64 * kb; LAS const unsigned char* vp = wl + ML_V + trN + 16 * sp * 144 + 64 * vb;
;                       X[kb][vb] = MFMA32(cat8(tr_read(kp), tr_read(kp + 4 * 144)), cat8(tr_read(vp), tr_read(vp + 4 * 144)), X[kb][vb]); } }
;           float dn = 0.f;
; #pragma unroll 8
;           for (int s2 = 0; s2 < 32; ++s2) dn += bf2f(*(LAS const unsigned short*)(wl + ML_WK + s2 * 144 + 2 * lane));
;           nk = eg * nk + dn; nl[lane] = nk; }
.LBB0_792:
	ds_read_u16 v126, v221
	ds_read_u16 v127, v221 offset:144
	ds_read_u16 v128, v221 offset:288
	ds_read_u16 v129, v221 offset:432
	ds_read_u16 v130, v221 offset:576
	ds_read_u16 v131, v221 offset:720
	ds_read_u16 v132, v221 offset:864
	ds_read_u16 v133, v221 offset:1008
	ds_read_u16 v134, v221 offset:1152
	ds_read_u16 v135, v221 offset:1296
	ds_read_u16 v136, v221 offset:1440
	ds_read_u16 v137, v221 offset:1584
	ds_read_u16 v138, v221 offset:1728
	ds_read_u16 v139, v221 offset:1872
	ds_read_u16 v166, v221 offset:2016
	ds_read_u16 v167, v221 offset:2160
	ds_read_u16 v168, v221 offset:2304
	ds_read_u16 v169, v221 offset:2448
	ds_read_u16 v170, v221 offset:2592
	ds_read_u16 v171, v221 offset:2736
	ds_read_u16 v172, v221 offset:2880
	ds_read_u16 v173, v221 offset:3024
	ds_read_u16 v174, v221 offset:3168
	ds_read_u16 v175, v221 offset:3312
	ds_read_u16 v176, v221 offset:3456
	ds_read_u16 v177, v221 offset:3600
	ds_read_u16 v178, v221 offset:3744
	ds_read_u16 v179, v221 offset:3888
	ds_read_u16 v180, v221 offset:4032
	ds_read_u16 v181, v221 offset:4176
	ds_read_u16 v182, v221 offset:4320
	ds_read_u16 v233, v221 offset:4464
	s_waitcnt lgkmcnt(15)
	v_lshlrev_b32_e32 v126, 16, v126
	v_add_f32_e32 v2, v2, v126
	v_lshlrev_b32_e32 v127, 16, v127
	v_add_f32_e32 v2, v2, v127
	v_lshlrev_b32_e32 v128, 16, v128
	v_add_f32_e32 v2, v2, v128
	v_lshlrev_b32_e32 v129, 16, v129
	v_add_f32_e32 v2, v2, v129
	v_lshlrev_b32_e32 v130, 16, v130
	v_add_f32_e32 v2, v2, v130
	v_lshlrev_b32_e32 v131, 16, v131
	v_add_f32_e32 v2, v2, v131
	v_lshlrev_b32_e32 v132, 16, v132
	v_add_f32_e32 v2, v2, v132
	v_lshlrev_b32_e32 v133, 16, v133
	v_add_f32_e32 v2, v2, v133
	v_lshlrev_b32_e32 v134, 16, v134
	v_add_f32_e32 v2, v2, v134
	v_lshlrev_b32_e32 v135, 16, v135
	v_add_f32_e32 v2, v2, v135
	v_lshlrev_b32_e32 v136, 16, v136
	v_add_f32_e32 v2, v2, v136
	v_lshlrev_b32_e32 v137, 16, v137
	v_add_f32_e32 v2, v2, v137
	v_lshlrev_b32_e32 v138, 16, v138
	v_add_f32_e32 v2, v2, v138
	v_lshlrev_b32_e32 v139, 16, v139
	v_add_f32_e32 v2, v2, v139
	v_lshlrev_b32_e32 v166, 16, v166
	v_add_f32_e32 v2, v2, v166
	v_lshlrev_b32_e32 v167, 16, v167
	v_add_f32_e32 v2, v2, v167
	s_waitcnt lgkmcnt(15)
	v_lshlrev_b32_e32 v168, 16, v168
	v_add_f32_e32 v2, v2, v168
	s_waitcnt lgkmcnt(14)
	v_lshlrev_b32_e32 v169, 16, v169
	v_add_f32_e32 v2, v2, v169
	s_waitcnt lgkmcnt(13)
	v_lshlrev_b32_e32 v170, 16, v170
	v_add_f32_e32 v2, v2, v170
	s_waitcnt lgkmcnt(12)
	v_lshlrev_b32_e32 v171, 16, v171
	v_add_f32_e32 v2, v2, v171
	s_waitcnt lgkmcnt(11)
	v_lshlrev_b32_e32 v172, 16, v172
	v_add_f32_e32 v2, v2, v172
	s_waitcnt lgkmcnt(10)
	v_lshlrev_b32_e32 v173, 16, v173
	v_add_f32_e32 v2, v2, v173
	s_waitcnt lgkmcnt(9)
	v_lshlrev_b32_e32 v174, 16, v174
	v_add_f32_e32 v2, v2, v174
	s_waitcnt lgkmcnt(8)
	v_lshlrev_b32_e32 v175, 16, v175
	v_add_f32_e32 v2, v2, v175
	s_waitcnt lgkmcnt(7)
	v_lshlrev_b32_e32 v176, 16, v176
	v_add_f32_e32 v2, v2, v176
	s_waitcnt lgkmcnt(6)
	v_lshlrev_b32_e32 v177, 16, v177
	v_add_f32_e32 v2, v2, v177
	s_waitcnt lgkmcnt(5)
	v_lshlrev_b32_e32 v178, 16, v178
	v_add_f32_e32 v2, v2, v178
	s_waitcnt lgkmcnt(4)
	v_lshlrev_b32_e32 v179, 16, v179
	v_add_f32_e32 v2, v2, v179
	s_waitcnt lgkmcnt(3)
	v_lshlrev_b32_e32 v180, 16, v180
	v_add_f32_e32 v2, v2, v180
	s_waitcnt lgkmcnt(2)
	v_lshlrev_b32_e32 v181, 16, v181
	v_add_f32_e32 v2, v2, v181
	s_waitcnt lgkmcnt(1)
	v_lshlrev_b32_e32 v182, 16, v182
	v_add_f32_e32 v2, v2, v182
	s_waitcnt lgkmcnt(0)
	v_lshlrev_b32_e32 v233, 16, v233
	v_add_f32_e32 v2, v2, v233
	v_pk_mul_f32 v[18:19], v[18:19], v[110:111]
	v_pk_mul_f32 v[16:17], v[16:17], v[108:109]
	v_pk_mul_f32 v[14:15], v[14:15], v[106:107]
	v_pk_mul_f32 v[12:13], v[12:13], v[104:105]
	v_pk_mul_f32 v[10:11], v[10:11], v[102:103]
	v_pk_mul_f32 v[8:9], v[8:9], v[100:101]
	v_pk_mul_f32 v[6:7], v[6:7], v[98:99]
	v_pk_mul_f32 v[4:5], v[4:5], v[96:97]
	v_pk_mul_f32 v[50:51], v[50:51], v[110:111]
	v_pk_mul_f32 v[48:49], v[48:49], v[108:109]
	v_pk_mul_f32 v[46:47], v[46:47], v[106:107]
	v_pk_mul_f32 v[44:45], v[44:45], v[104:105]
	v_pk_mul_f32 v[42:43], v[42:43], v[102:103]
	v_pk_mul_f32 v[40:41], v[40:41], v[100:101]
	v_pk_mul_f32 v[38:39], v[38:39], v[98:99]
	v_pk_mul_f32 v[36:37], v[36:37], v[96:97]
	v_mfma_f32_32x32x16_bf16 v[4:19], v[76:79], v[68:71], v[4:19]
	v_fmac_f32_e32 v2, v226, v96
	s_add_i32 s50, s50, 1
	s_cmp_eq_u32 s50, 4
	v_mov_b32_e32 v226, v2
	ds_write_b32 v149, v2 offset:16896
	v_mfma_f32_32x32x16_bf16 v[36:51], v[88:91], v[68:71], v[36:51]
	v_mfma_f32_32x32x16_bf16 v[4:19], v[80:83], v[72:75], v[4:19]
	v_mfma_f32_32x32x16_bf16 v[36:51], v[92:95], v[72:75], v[36:51]
	v_mfma_f32_32x32x16_bf16 v[52:67], v[92:95], v[84:87], v[52:67]
	s_cbranch_scc0 .LBB0_787
	s_setprio 0
	s_mov_b64 s[92:93], 0x80
	s_mov_b32 s48, s2

; #define LAS __attribute__((address_space(3)))
; template <bool OUT>
; __device__ __forceinline__ void mlstm_item(const bf16* u, bf16* y, float* scratch, const float* convw, const float* ib, const float* fbias, const float* normw, LAS unsigned char* wl, int bh, int c, int lane) {
;     const int b = bh / 6, h = bh % 6, r = lane & 31, hi = lane >> 5;
;     const bf16* ub = u + (size_t)b * S * NU;
;     LAS float* cw = (LAS float*)(wl + ML_CW); LAS float* eb = (LAS float*)(wl + ML_EB); LAS float* nl = (LAS float*)(wl + ML_NL); LAS float* nwl = (LAS float*)(wl + ML_NW);
;     for (int i = lane; i < 512; i += 64) { const int tap = i >> 7, ch = i & 127; cw[i] = convw[tap * 768 + (ch < 64 ? (64 * h + ch) : (384 + 64 * h + (ch - 64)))]; }
;     if (OUT) nwl[lane] = normw[h * 64 + lane];
;     const float ibh = ib[h], fbh = fbias[h];
;     f32x16 X[2][2];
; #pragma unroll
;     for (int a = 0; a < 2; ++a)
; #pragma unroll
;         for (int bb = 0; bb < 2; ++bb)
; #pragma unroll
;             for (int i = 0; i < 16; ++i) X[a][bb][i] = 0.f;
;     float nk = 0.f, Gsum = 0.f;
;     if (OUT) {
;         float dec = 1.f;
;     ...
;             const float* s0 = scratch + (size_t)(bh * 16 + cp) * ML_ITEM_F;
;             f32x16 v0[4];
; #pragma unroll
;             for (int blk = 0; blk < 4; ++blk) v0[blk] = *(const f32x16*)(s0 + blk * 1024 + lane * 16);
;             const float n0 = s0[4096 + lane], g0 = s0[4160];
; #pragma unroll
;             for (int blk = 0; blk < 4; ++blk) X[blk >> 1][blk & 1] += v0[blk] * dec;
;             nk += dec * n0;
;             dec *= __expf(g0);
;         }
;     }
;     nl[lane] = nk;
.LBB0_803:
	v_add_u32_e32 v8, s33, v202
	v_lshlrev_b32_e32 v8, 2, v8
	v_add_u32_e32 v9, 0x1000, v8
	v_add_u32_e32 v10, 0x2000, v8
	v_add_u32_e32 v11, 0x3000, v8
	global_load_dword v12, v8, s[44:45] offset:2048
	global_load_dword v13, v8, s[44:45] offset:3584
	global_load_dword v14, v9, s[44:45] offset:1024
	global_load_dword v15, v9, s[44:45] offset:2560
	global_load_dword v16, v10, s[44:45]
	global_load_dword v17, v10, s[44:45] offset:1536
	global_load_dword v18, v10, s[44:45] offset:3072
	global_load_dword v19, v11, s[44:45] offset:512
	s_waitcnt vmcnt(7)
	ds_write_b32 v1, v12
	s_waitcnt vmcnt(6)
	ds_write_b32 v1, v13 offset:256
	s_waitcnt vmcnt(5)
	ds_write_b32 v1, v14 offset:512
	s_waitcnt vmcnt(4)
	ds_write_b32 v1, v15 offset:768
	s_waitcnt vmcnt(3)
	ds_write_b32 v1, v16 offset:1024
	s_waitcnt vmcnt(2)
	ds_write_b32 v1, v17 offset:1280
	s_waitcnt vmcnt(1)
	ds_write_b32 v1, v18 offset:1536
	s_waitcnt vmcnt(0)
	ds_write_b32 v1, v19 offset:1792
	s_or_b64 exec, exec, s[0:1]
	s_mul_i32 s3, s3, 15
	s_sub_i32 s0, s98, s3
	s_and_b32 s3, s0, 0xff
	s_mul_i32 s51, s51, 0xe00000
	v_readlane_b32 s0, v253, 45
	v_readlane_b32 s1, v253, 46
	s_add_u32 s0, s0, s51
	s_addc_u32 s1, s1, 0
	s_lshl_b32 s51, s50, 2
	v_mov_b32_e32 v2, s51
	global_load_dword v1, v2, s[44:45] offset:32
	global_load_dword v118, v2, s[44:45] offset:64
	s_lshl_b32 s52, s3, 7
	s_lshl_b32 s50, s50, 1
	s_add_u32 s86, s0, s50
	s_addc_u32 s87, s1, 0
	s_lshl_b32 s50, s33, 1
	s_add_u32 s50, s0, s50
	s_addc_u32 s51, s1, 0
	v_lshlrev_b32_e32 v2, 1, v148
	v_lshl_add_u64 v[102:103], s[50:51], 0, v[2:3]
	v_and_b32_e32 v2, 0x60, v214
	v_add_u32_e32 v4, -1, v214
	v_cmp_lt_i32_e32 vcc, v4, v2
	v_mov_b32_e32 v52, 0
	v_lshl_or_b32 v119, v214, 2, v217
	v_cndmask_b32_e32 v4, v4, v214, vcc
	v_lshlrev_b32_e32 v120, 2, v4
	v_add_u32_e32 v4, -2, v214
	v_cmp_lt_i32_e32 vcc, v4, v2
	s_mov_b32 s53, 0
	s_lshl_b32 s84, s33, 1
	v_cndmask_b32_e32 v4, v4, v214, vcc
	v_lshlrev_b32_e32 v121, 2, v4
	v_add_u32_e32 v4, -4, v214
	v_cmp_lt_i32_e32 vcc, v4, v2
	v_mov_b32_e32 v53, v52
	v_mov_b32_e32 v54, v52
	v_cndmask_b32_e32 v4, v4, v214, vcc
	v_lshlrev_b32_e32 v122, 2, v4
	v_add_u32_e32 v4, -8, v214
	v_cmp_lt_i32_e32 vcc, v4, v2
	v_mov_b32_e32 v55, v52
	v_mov_b32_e32 v56, v52
	v_cndmask_b32_e32 v4, v4, v214, vcc
	v_lshlrev_b32_e32 v123, 2, v4
	v_add_u32_e32 v4, -16, v214
	v_cmp_lt_i32_e32 vcc, v4, v2
	v_mov_b32_e32 v57, v52
	v_mov_b32_e32 v58, v52
	v_cndmask_b32_e32 v2, v4, v214, vcc
	v_lshlrev_b32_e32 v124, 2, v2
	v_mov_b32_e32 v59, v52
	v_mov_b32_e32 v60, v52
	v_mov_b32_e32 v61, v52
	v_mov_b32_e32 v62, v52
	v_mov_b32_e32 v63, v52
	v_mov_b32_e32 v64, v52
	v_mov_b32_e32 v65, v52
	v_mov_b32_e32 v66, v52
	v_mov_b32_e32 v67, v52
	v_mov_b32_e32 v36, v52
	v_mov_b32_e32 v37, v52
	v_mov_b32_e32 v38, v52
	v_mov_b32_e32 v39, v52
	v_mov_b32_e32 v40, v52
	v_mov_b32_e32 v41, v52
	v_mov_b32_e32 v42, v52
	v_mov_b32_e32 v43, v52
	v_mov_b32_e32 v44, v52
	v_mov_b32_e32 v45, v52
	v_mov_b32_e32 v46, v52
	v_mov_b32_e32 v47, v52
	v_mov_b32_e32 v48, v52
	v_mov_b32_e32 v49, v52
	v_mov_b32_e32 v50, v52
	v_mov_b32_e32 v51, v52
	v_mov_b32_e32 v20, v52
	v_mov_b32_e32 v21, v52
	v_mov_b32_e32 v22, v52
	v_mov_b32_e32 v23, v52
	v_mov_b32_e32 v24, v52
	v_mov_b32_e32 v25, v52
	v_mov_b32_e32 v26, v52
	v_mov_b32_e32 v27, v52
	v_mov_b32_e32 v28, v52
	v_mov_b32_e32 v29, v52
	v_mov_b32_e32 v30, v52
	v_mov_b32_e32 v31, v52
	v_mov_b32_e32 v32, v52
	v_mov_b32_e32 v33, v52
	v_mov_b32_e32 v34, v52
	v_mov_b32_e32 v35, v52
	v_mov_b32_e32 v4, v52
	v_mov_b32_e32 v5, v52
	v_mov_b32_e32 v6, v52
	v_mov_b32_e32 v7, v52
	v_mov_b32_e32 v8, v52
	v_mov_b32_e32 v9, v52
	v_mov_b32_e32 v10, v52
	v_mov_b32_e32 v11, v52
	v_mov_b32_e32 v12, v52
	v_mov_b32_e32 v13, v52
	v_mov_b32_e32 v14, v52
	v_mov_b32_e32 v15, v52
	v_mov_b32_e32 v16, v52
	v_mov_b32_e32 v17, v52
	v_mov_b32_e32 v18, v52
	v_mov_b32_e32 v19, v52
	v_mov_b32_e32 v100, v52
	v_mov_b32_e32 v101, v52
	ds_write_b32 v149, v3 offset:16896

; #define LAS __attribute__((address_space(3)))
; __device__ __forceinline__ float bf2f(unsigned short v) { return __uint_as_float(((unsigned)v) << 16); }
; __device__ __forceinline__ float lo_f(unsigned w) { return __uint_as_float(w << 16); }
; __device__ __forceinline__ float hi_f(unsigned w) { return __uint_as_float(w & 0xffff0000u); }
; __device__ __forceinline__ s16x4 tr_read(LAS const unsigned char* p) { return __builtin_bit_cast(s16x4, __builtin_amdgcn_ds_read_tr16_b64_v4i16((LAS s16x4*)p)); }
; __device__ __forceinline__ s16x8 cat8(s16x4 a, s16x4 b) { return (s16x8){a[0], a[1], a[2], a[3], b[0], b[1], b[2], b[3]}; }
; __device__ __forceinline__ unsigned cvtpk(float lo, float hi) { return pg8::cvt_pk_bf16(lo, hi); }
; #define MFMA32(a, b, c) __builtin_amdgcn_mfma_f32_32x32x16_bf16(a, b, c, 0, 0, 0)
; template <bool OUT>
; __device__ __forceinline__ void mlstm_item(const bf16* u, bf16* y, float* scratch, const float* convw, const float* ib, const float* fbias, const float* normw, LAS unsigned char* wl, int bh, int c, int lane) {
;     ...
;         { const float wsc = __expf(g + es), eg = __expf(g);
; #pragma unroll
;           for (int f = 0; f < 4; ++f) { const v4u kw = __builtin_bit_cast(v4u, Kf[f]);
; #pragma unroll
;               for (int e = 0; e < 2; ++e) { const unsigned k0 = e ? kw.z : kw.x, k1 = e ? kw.w : kw.y; const int ch = 16 * f + 8 * e + 4 * hi;
;                   *(LAS unsigned long long*)(wl + ML_WK + r * 144 + ch * 2) = (unsigned long long)cvtpk(lo_f(k0) * wsc, hi_f(k0) * wsc) | ((unsigned long long)cvtpk(lo_f(k1) * wsc, hi_f(k1) * wsc) << 32); } }
; #pragma unroll
;           for (int kb = 0; kb < 2; ++kb)
; #pragma unroll
;               for (int vb = 0; vb < 2; ++vb) { X[kb][vb] *= eg;
; #pragma unroll
;                   for (int sp = 0; sp < 2; ++sp) { LAS const unsigned char* kp = wl + ML_WK + trN + 16 * sp * 144 + 64 * kb; LAS const unsigned char* vp = wl + ML_V + trN + 16 * sp * 144 + 64 * vb;
;                       X[kb][vb] = MFMA32(cat8(tr_read(kp), tr_read(kp + 4 * 144)), cat8(tr_read(vp), tr_read(vp + 4 * 144)), X[kb][vb]); } }
;           float dn = 0.f;
; #pragma unroll 8
;           for (int s2 = 0; s2 < 32; ++s2) dn += bf2f(*(LAS const unsigned short*)(wl + ML_WK + s2 * 144 + 2 * lane));
;           nk = eg * nk + dn; nl[lane] = nk; }
.LBB0_810:
	ds_read_u16 v125, v221
	ds_read_u16 v126, v221 offset:144
	ds_read_u16 v127, v221 offset:288
	ds_read_u16 v128, v221 offset:432
	ds_read_u16 v129, v221 offset:576
	ds_read_u16 v130, v221 offset:720
	ds_read_u16 v131, v221 offset:864
	ds_read_u16 v132, v221 offset:1008
	ds_read_u16 v133, v221 offset:1152
	ds_read_u16 v134, v221 offset:1296
	ds_read_u16 v135, v221 offset:1440
	ds_read_u16 v136, v221 offset:1584
	ds_read_u16 v137, v221 offset:1728
	ds_read_u16 v138, v221 offset:1872
	ds_read_u16 v139, v221 offset:2016
	ds_read_u16 v162, v221 offset:2160
	ds_read_u16 v163, v221 offset:2304
	ds_read_u16 v164, v221 offset:2448
	ds_read_u16 v165, v221 offset:2592
	ds_read_u16 v166, v221 offset:2736
	ds_read_u16 v167, v221 offset:2880
	ds_read_u16 v168, v221 offset:3024
	ds_read_u16 v169, v221 offset:3168
	ds_read_u16 v170, v221 offset:3312
	ds_read_u16 v171, v221 offset:3456
	ds_read_u16 v172, v221 offset:3600
	ds_read_u16 v173, v221 offset:3744
	ds_read_u16 v174, v221 offset:3888
	ds_read_u16 v175, v221 offset:4032
	ds_read_u16 v176, v221 offset:4176
	ds_read_u16 v177, v221 offset:4320
	ds_read_u16 v178, v221 offset:4464
	s_waitcnt lgkmcnt(15)
	v_lshlrev_b32_e32 v125, 16, v125
	v_add_f32_e32 v104, v104, v125
	v_lshlrev_b32_e32 v126, 16, v126
	v_add_f32_e32 v104, v104, v126
	v_lshlrev_b32_e32 v127, 16, v127
	v_add_f32_e32 v104, v104, v127
	v_lshlrev_b32_e32 v128, 16, v128
	v_add_f32_e32 v104, v104, v128
	v_lshlrev_b32_e32 v129, 16, v129
	v_add_f32_e32 v104, v104, v129
	v_lshlrev_b32_e32 v130, 16, v130
	v_add_f32_e32 v104, v104, v130
	v_lshlrev_b32_e32 v131, 16, v131
	v_add_f32_e32 v104, v104, v131
	v_lshlrev_b32_e32 v132, 16, v132
	v_add_f32_e32 v104, v104, v132
	v_lshlrev_b32_e32 v133, 16, v133
	v_add_f32_e32 v104, v104, v133
	v_lshlrev_b32_e32 v134, 16, v134
	v_add_f32_e32 v104, v104, v134
	v_lshlrev_b32_e32 v135, 16, v135
	v_add_f32_e32 v104, v104, v135
	v_lshlrev_b32_e32 v136, 16, v136
	v_add_f32_e32 v104, v104, v136
	v_lshlrev_b32_e32 v137, 16, v137
	v_add_f32_e32 v104, v104, v137
	v_lshlrev_b32_e32 v138, 16, v138
	v_add_f32_e32 v104, v104, v138
	v_lshlrev_b32_e32 v139, 16, v139
	v_add_f32_e32 v104, v104, v139
	v_lshlrev_b32_e32 v162, 16, v162
	v_add_f32_e32 v104, v104, v162
	s_waitcnt lgkmcnt(15)
	v_lshlrev_b32_e32 v163, 16, v163
	v_add_f32_e32 v104, v104, v163
	s_waitcnt lgkmcnt(14)
	v_lshlrev_b32_e32 v164, 16, v164
	v_add_f32_e32 v104, v104, v164
	s_waitcnt lgkmcnt(13)
	v_lshlrev_b32_e32 v165, 16, v165
	v_add_f32_e32 v104, v104, v165
	s_waitcnt lgkmcnt(12)
	v_lshlrev_b32_e32 v166, 16, v166
	v_add_f32_e32 v104, v104, v166
	s_waitcnt lgkmcnt(11)
	v_lshlrev_b32_e32 v167, 16, v167
	v_add_f32_e32 v104, v104, v167
	s_waitcnt lgkmcnt(10)
	v_lshlrev_b32_e32 v168, 16, v168
	v_add_f32_e32 v104, v104, v168
	s_waitcnt lgkmcnt(9)
	v_lshlrev_b32_e32 v169, 16, v169
	v_add_f32_e32 v104, v104, v169
	s_waitcnt lgkmcnt(8)
	v_lshlrev_b32_e32 v170, 16, v170
	v_add_f32_e32 v104, v104, v170
	s_waitcnt lgkmcnt(7)
	v_lshlrev_b32_e32 v171, 16, v171
	v_add_f32_e32 v104, v104, v171
	s_waitcnt lgkmcnt(6)
	v_lshlrev_b32_e32 v172, 16, v172
	v_add_f32_e32 v104, v104, v172
	s_waitcnt lgkmcnt(5)
	v_lshlrev_b32_e32 v173, 16, v173
	v_add_f32_e32 v104, v104, v173
	s_waitcnt lgkmcnt(4)
	v_lshlrev_b32_e32 v174, 16, v174
	v_add_f32_e32 v104, v104, v174
	s_waitcnt lgkmcnt(3)
	v_lshlrev_b32_e32 v175, 16, v175
	v_add_f32_e32 v104, v104, v175
	s_waitcnt lgkmcnt(2)
	v_lshlrev_b32_e32 v176, 16, v176
	v_add_f32_e32 v104, v104, v176
	s_waitcnt lgkmcnt(1)
	v_lshlrev_b32_e32 v177, 16, v177
	v_add_f32_e32 v104, v104, v177
	s_waitcnt lgkmcnt(0)
	v_lshlrev_b32_e32 v178, 16, v178
	v_add_f32_e32 v104, v104, v178
	v_pk_mul_f32 v[66:67], v[66:67], v[116:117]
	v_pk_mul_f32 v[64:65], v[64:65], v[114:115]
	v_pk_mul_f32 v[62:63], v[62:63], v[112:113]
	v_pk_mul_f32 v[60:61], v[60:61], v[110:111]
	v_pk_mul_f32 v[58:59], v[58:59], v[108:109]
	v_pk_mul_f32 v[56:57], v[56:57], v[106:107]
	v_pk_mul_f32 v[54:55], v[54:55], v[98:99]
	v_pk_mul_f32 v[52:53], v[52:53], v[96:97]
	v_pk_mul_f32 v[34:35], v[34:35], v[116:117]
	v_pk_mul_f32 v[32:33], v[32:33], v[114:115]
	v_pk_mul_f32 v[30:31], v[30:31], v[112:113]
	v_pk_mul_f32 v[28:29], v[28:29], v[110:111]
	v_pk_mul_f32 v[26:27], v[26:27], v[108:109]
	v_pk_mul_f32 v[24:25], v[24:25], v[106:107]
	v_pk_mul_f32 v[22:23], v[22:23], v[98:99]
	v_pk_mul_f32 v[20:21], v[20:21], v[96:97]
	v_mfma_f32_32x32x16_bf16 v[52:67], v[80:83], v[76:79], v[52:67]
	v_mul_f32_e32 v100, v100, v96
	s_add_i32 s53, s53, 1
	v_add_f32_e64 v100, v100, v104
	v_add_f32_e64 v101, v101, v105
	s_cmp_eq_u32 s53, 4
	ds_write_b32 v149, v100 offset:16896
	v_mfma_f32_32x32x16_bf16 v[20:35], v[88:91], v[76:79], v[20:35]
	v_mfma_f32_32x32x16_bf16 v[52:67], v[84:87], v[92:95], v[52:67]
	v_mfma_f32_32x32x16_bf16 v[20:35], v[72:75], v[92:95], v[20:35]
	v_mfma_f32_32x32x16_bf16 v[4:19], v[72:75], v[68:71], v[4:19]
	s_cbranch_scc0 .LBB0_805
; __device__ __forceinline__ void st_wt64(float* p, float a, float b) { __hip_atomic_store((unsigned long long*)p, ((unsigned long long)__float_as_uint(b) << 32) | (unsigned long long)__float_as_uint(a), __ATOMIC_RELAXED, __HIP_MEMORY_SCOPE_AGENT); }
; __device__ __forceinline__ void st_wt32(float* p, float a) { __hip_atomic_store((unsigned*)p, __float_as_uint(a), __ATOMIC_RELAXED, __HIP_MEMORY_SCOPE_AGENT); }
; template <bool OUT>
; __device__ __forceinline__ void mlstm_item(const bf16* u, bf16* y, float* scratch, const float* convw, const float* ib, const float* fbias, const float* normw, LAS unsigned char* wl, int bh, int c, int lane) {
;     ...
;     if (!OUT) {
;         float* sp = scratch + (size_t)(bh * 16 + c) * ML_ITEM_F;
; #pragma unroll
;         for (int blk = 0; blk < 4; ++blk) {
; #pragma unroll
;             for (int i = 0; i < 8; ++i) st_wt64(sp + blk * 1024 + lane * 16 + 2 * i, X[blk >> 1][blk & 1][2 * i], X[blk >> 1][blk & 1][2 * i + 1]); }
;         st_wt32(sp + 4096 + lane, nk);
;         if (lane == 0) st_wt32(sp + 4160, Gsum);
	s_lshl_b32 s0, s2, 4
	s_or_b32 s0, s0, s3
	s_mul_i32 s84, s0, 0x1080
	s_lshl_b64 s[0:1], s[84:85], 2
	s_add_u32 s0, s60, s0
	s_addc_u32 s1, s61, s1
	v_lshl_add_u64 v[68:69], v[142:143], 2, s[0:1]
	s_nop 1
	global_store_dwordx2 v[68:69], v[52:53], off sc1
	global_store_dwordx2 v[68:69], v[54:55], off offset:8 sc1
	global_store_dwordx2 v[68:69], v[56:57], off offset:16 sc1
	global_store_dwordx2 v[68:69], v[58:59], off offset:24 sc1
	global_store_dwordx2 v[68:69], v[60:61], off offset:32 sc1
	global_store_dwordx2 v[68:69], v[62:63], off offset:40 sc1
	global_store_dwordx2 v[68:69], v[64:65], off offset:48 sc1
	global_store_dwordx2 v[68:69], v[66:67], off offset:56 sc1
	v_add_co_u32_e32 v52, vcc, s72, v68
	s_movk_i32 s2, 0x3000
	s_nop 0
	v_addc_co_u32_e32 v53, vcc, 0, v69, vcc
	v_add_co_u32_e32 v54, vcc, s83, v68
	s_nop 1
	v_addc_co_u32_e32 v55, vcc, 0, v69, vcc
	global_store_dwordx2 v[54:55], v[36:37], off offset:-4096 sc1
	global_store_dwordx2 v[52:53], v[38:39], off offset:8 sc1
	global_store_dwordx2 v[52:53], v[40:41], off offset:16 sc1
	global_store_dwordx2 v[52:53], v[42:43], off offset:24 sc1
	global_store_dwordx2 v[52:53], v[44:45], off offset:32 sc1
	global_store_dwordx2 v[52:53], v[46:47], off offset:40 sc1
	global_store_dwordx2 v[52:53], v[48:49], off offset:48 sc1
	global_store_dwordx2 v[52:53], v[50:51], off offset:56 sc1
	global_store_dwordx2 v[54:55], v[20:21], off sc1
	global_store_dwordx2 v[54:55], v[22:23], off offset:8 sc1
	global_store_dwordx2 v[54:55], v[24:25], off offset:16 sc1
	global_store_dwordx2 v[54:55], v[26:27], off offset:24 sc1
	global_store_dwordx2 v[54:55], v[28:29], off offset:32 sc1
	global_store_dwordx2 v[54:55], v[30:31], off offset:40 sc1
	global_store_dwordx2 v[54:55], v[32:33], off offset:48 sc1
	global_store_dwordx2 v[54:55], v[34:35], off offset:56 sc1
	v_add_co_u32_e32 v20, vcc, s2, v68
	s_nop 1
	v_addc_co_u32_e32 v21, vcc, 0, v69, vcc
	global_store_dwordx2 v[20:21], v[4:5], off sc1
	global_store_dwordx2 v[20:21], v[6:7], off offset:8 sc1
	global_store_dwordx2 v[20:21], v[8:9], off offset:16 sc1
	global_store_dwordx2 v[20:21], v[10:11], off offset:24 sc1
	global_store_dwordx2 v[20:21], v[12:13], off offset:32 sc1
	global_store_dwordx2 v[20:21], v[14:15], off offset:40 sc1
	global_store_dwordx2 v[20:21], v[16:17], off offset:48 sc1
	global_store_dwordx2 v[20:21], v[18:19], off offset:56 sc1
	v_lshl_add_u64 v[4:5], v[202:203], 2, s[0:1]
	v_add_co_u32_e32 v4, vcc, 0x4000, v4
	s_nop 1
	v_addc_co_u32_e32 v5, vcc, 0, v5, vcc
	global_store_dword v[4:5], v100, off sc1
	s_and_saveexec_b64 s[50:51], s[58:59]
	s_cbranch_execz .LBB0_814
	global_store_dword v209, v101, s[0:1] offset:256 sc1
